# sample-row small tiles (gemm_tile<2>, E4/O5 tail): 3-stage LDS-DMA pipeline with counted vmcnt(6), compact 3x24KB LDS layout
# baseline (speedup 1.0000x reference)
; template <int MT, class Epi>
; DI void gemm_tile(const u16* __restrict__ X, long ldx, const u16* __restrict__ W, long ldw, int K, char* smem,
;                   int m0, int n0, const Epi& epi, bool pre = false, const u16* Xn = nullptr, const u16* Wn = nullptr) {
;     ...
;   const int wu = __builtin_amdgcn_readfirstlane(wave);
;   const unsigned sbase = (unsigned)__builtin_amdgcn_readfirstlane((int)(unsigned)(size_t)smem);
;   const int r8 = lane >> 3, c0 = (lane & 7) ^ (r8 >> 1);
;   const long oxe = (long)(wu * MT * 8 + r8) * ldx + (c0 << 3), oxo = (long)(wu * MT * 8 + r8) * ldx + ((c0 ^ 4) << 3);
;   const long owe = (long)(wu * 32 + r8) * ldw + (c0 << 3), owo = (long)(wu * 32 + r8) * ldw + ((c0 ^ 4) << 3);
;   const u16 *xe = X + oxe, *xo = X + oxo, *we = W + owe, *wo = W + owo;
;   const long ldx8 = 8 * ldx, ldw8 = 8 * ldw;
;   const unsigned xdst = sbase + wu * MT * 1024, wdst = sbase + 16384 + wu * 4096;
;     ...
;   if (!pre) {
;     __syncthreads();
;     GT_DMA(0u)
;   } else {
;     xe += 64; xo += 64; we += 64; wo += 64;
;   }
;   const int nk = K >> 6;
;   int kt = 0;
;   do {
;     asm volatile("s_waitcnt vmcnt(0)" ::: "memory");
;     __syncthreads();
;     if (kt + 1 < nk) GT_DMA((unsigned)((kt + 1) & 1) * 32768u)
;     else if (Xn != nullptr) { xe = Xn + oxe; xo = Xn + oxo; we = Wn + owe; wo = Wn + owo; GT_DMA(0u) }
; DI void phase_odd(const Params& p, int o, int sub, char* smem) {
;     ...
;         const int u = t - 512, tm = u >> 3, tn = u & 7, m0 = M_PROMPT + tm * 64;
;         gemm_tile<2>(ao + (size_t)m0 * 1024, 1024, W + WO_O + (size_t)tn * 128 * 1024, 1024, 1024, smem, m0, tn * 128, epi);
.LBB0_26:
	s_and_b32 s7, s4, 7
	s_lshl_b32 s34, s7, 18
	s_cmpk_gt_i32 s6, 0x1ff
	s_mov_b64 s[38:39], -1
	s_cbranch_scc0 .LBB0_30
	s_bfe_u32 s8, s5, 0x190006
	s_mov_b32 s9, s35
	s_lshl_b64 s[12:13], s[8:9], 17
	s_lshl_b32 s8, s6, 3
	s_and_b32 s8, s8, 0x7fffffc0
	s_add_i32 s38, s8, 0x3000
	s_mov_b32 s39, s35
	s_and_b32 s7, s6, 7
	s_lshl_b64 s[8:9], s[38:39], 11
	v_readlane_b32 s10, v252, 24
	v_mov_b32_e32 v1, v185
	v_readlane_b32 s11, v252, 25
	s_add_u32 s8, s10, s8
	s_addc_u32 s9, s11, s9
	v_ashrrev_i32_e32 v2, 6, v1
	v_bfe_u32 v4, v1, 3, 3
	v_readfirstlane_b32 s11, v2
	v_and_b32_e32 v40, 1, v2
	v_bfe_u32 v42, v1, 4, 2
	v_lshl_or_b32 v2, s11, 4, v4
	v_bitop3_b32 v8, v42, v1, 7 bitop3:0x78
	v_ashrrev_i32_e32 v3, 31, v2
	s_lshl_b32 s10, s7, 18
	v_readlane_b32 s16, v252, 26
	v_lshl_or_b32 v4, s11, 5, v4
	v_lshlrev_b64 v[2:3], 11, v[2:3]
	v_lshlrev_b32_e32 v182, 4, v8
	v_readlane_b32 s17, v252, 27
	s_add_u32 s14, s16, s10
	v_mov_b32_e32 v0, v183
	v_ashrrev_i32_e32 v5, 31, v4
	v_lshl_add_u64 v[6:7], s[8:9], 0, v[2:3]
	v_xor_b32_e32 v10, 64, v182
	v_mov_b32_e32 v11, v183
	s_addc_u32 s15, s17, 0
	v_lshl_add_u64 v[8:9], v[6:7], 0, v[182:183]
	v_lshl_add_u64 v[6:7], v[6:7], 0, v[10:11]
	v_lshlrev_b64 v[4:5], 11, v[4:5]
	s_lshl_b32 s8, s11, 11
	s_barrier
	s_mov_b32 m0, s8
	s_nop 0
	global_load_lds_dwordx4 v[8:9], off
	s_mov_b64 s[18:19], 0x4000
	v_lshl_add_u64 v[12:13], s[14:15], 0, v[4:5]
	s_lshl_b32 s11, s11, 12
	v_lshl_add_u64 v[6:7], v[6:7], 0, s[18:19]
	s_or_b32 s9, s8, 0x400
	s_mov_b32 m0, s9
	s_nop 0
	global_load_lds_dwordx4 v[6:7], off
	v_lshl_add_u64 v[14:15], v[12:13], 0, v[182:183]
	v_lshl_add_u64 v[6:7], v[12:13], 0, v[10:11]
	s_add_i32 s9, s11, 0x2000
	s_mov_b32 m0, s9
	s_nop 0
	global_load_lds_dwordx4 v[14:15], off
	v_lshl_add_u64 v[8:9], v[6:7], 0, s[18:19]
	s_add_i32 s14, s11, 0x2400
	s_mov_b32 m0, s14
	s_nop 0
	global_load_lds_dwordx4 v[8:9], off
	s_mov_b64 s[14:15], 0x8000
	v_lshl_add_u64 v[8:9], v[14:15], 0, s[14:15]
	s_add_i32 s14, s11, 0x2800
	s_mov_b32 m0, s14
	s_nop 0
	global_load_lds_dwordx4 v[8:9], off
	s_mov_b64 s[14:15], 0xc000
	s_waitcnt vmcnt(7)
	v_lshrrev_b32_e32 v16, 1, v1
	v_lshl_add_u64 v[6:7], v[6:7], 0, s[14:15]
	s_addk_i32 s11, 0x2c00
	s_mov_b32 m0, s11
	s_nop 0
	global_load_lds_dwordx4 v[6:7], off
	v_bitop3_b32 v6, v42, v16, 7 bitop3:0x78
	v_lshl_add_u64 v[4:5], s[34:35], 0, v[4:5]
	v_lshlrev_b32_e32 v48, 4, v6
	v_lshl_add_u64 v[6:7], v[4:5], 0, v[10:11]
	s_waitcnt vmcnt(4)
	v_lshl_add_u64 v[32:33], s[16:17], 0, v[6:7]
	v_readlane_b32 s16, v255, 5
	v_lshl_add_u64 v[4:5], v[4:5], 0, v[182:183]
	v_readlane_b32 s20, v255, 9
	v_readlane_b32 s21, v255, 10
	v_lshl_add_u64 v[2:3], s[12:13], 0, v[2:3]
	v_readlane_b32 s12, v254, 54
	v_lshl_add_u64 v[34:35], s[20:21], 0, v[4:5]
	v_bitop3_b32 v4, v2, v182, 64 bitop3:0xf6
	v_mov_b32_e32 v5, v3
	v_readlane_b32 s13, v254, 55
	v_and_b32_e32 v41, 15, v1
	v_ashrrev_i32_e32 v43, 7, v1
	v_bfe_u32 v1, v1, 1, 3
	v_lshl_add_u64 v[36:37], s[12:13], 0, v[4:5]
	v_readlane_b32 s12, v254, 57
	v_bitop3_b32 v1, v42, v1, 4 bitop3:0x36
	v_readlane_b32 s17, v255, 6
	v_or_b32_e32 v2, v2, v182
	v_readlane_b32 s13, v254, 58
	s_mov_b32 s10, 0
	v_lshlrev_b32_e32 v47, 12, v40
	v_lshlrev_b32_e32 v44, 7, v41
	v_lshlrev_b32_e32 v45, 13, v43
	v_lshlrev_b32_e32 v46, 4, v1
	v_lshl_add_u64 v[38:39], s[12:13], 0, v[2:3]
	s_mov_b64 s[40:41], 0
	v_mov_b32_e32 v1, v0
	v_mov_b32_e32 v2, v0
	v_mov_b32_e32 v3, v0
	v_mov_b32_e32 v4, v0
	v_mov_b32_e32 v5, v0
	v_mov_b32_e32 v6, v0
	v_mov_b32_e32 v7, v0
	v_mov_b32_e32 v8, v0
	v_mov_b32_e32 v9, v0
	v_mov_b32_e32 v10, v0
	v_mov_b32_e32 v11, v0
	v_mov_b32_e32 v12, v0
	v_mov_b32_e32 v13, v0
	v_mov_b32_e32 v14, v0
	v_mov_b32_e32 v15, v0
	v_mov_b32_e32 v16, v0
	v_mov_b32_e32 v17, v0
	v_mov_b32_e32 v18, v0
	v_mov_b32_e32 v19, v0
	v_mov_b32_e32 v20, v0
	v_mov_b32_e32 v21, v0
	v_mov_b32_e32 v22, v0
	v_mov_b32_e32 v23, v0
	v_mov_b32_e32 v24, v0
	v_mov_b32_e32 v25, v0
	v_mov_b32_e32 v26, v0
	v_mov_b32_e32 v27, v0
	v_mov_b32_e32 v28, v0
	v_mov_b32_e32 v29, v0
	v_mov_b32_e32 v30, v0
	v_mov_b32_e32 v31, v0
	s_mov_b64 s[16:17], 0x5a0080
	v_readlane_b32 s18, v255, 7
	v_readlane_b32 s19, v255, 8
	v_readlane_b32 s22, v255, 11
	v_readlane_b32 s23, v255, 12
	s_mov_b32 s12, 0x6000
	v_lshl_add_u64 v[54:55], v[36:37], 0, s[40:41]
	v_lshl_add_u64 v[56:57], v[38:39], 0, s[40:41]
	s_add_i32 s13, s12, s8
	s_mov_b32 m0, s13
	s_nop 0
	global_load_lds_dwordx4 v[56:57], off
	v_lshl_add_u64 v[52:53], v[34:35], 0, s[40:41]
	v_lshl_add_u64 v[54:55], v[54:55], 0, s[94:95]
	s_addk_i32 s13, 0x400
	s_mov_b32 m0, s13
	s_nop 0
	global_load_lds_dwordx4 v[54:55], off
	v_lshl_add_u64 v[50:51], v[32:33], 0, s[40:41]
	v_lshl_add_u64 v[58:59], v[52:53], 0, s[16:17]
	s_add_i32 s12, s12, s9
	s_mov_b32 m0, s12
	s_nop 0
	global_load_lds_dwordx4 v[58:59], off
	v_lshl_add_u64 v[54:55], v[50:51], 0, s[94:95]
	s_add_i32 s13, s12, 0x400
	s_mov_b32 m0, s13
	s_nop 0
	global_load_lds_dwordx4 v[54:55], off
	v_lshl_add_u64 v[52:53], v[52:53], 0, s[66:67]
	s_add_i32 s13, s12, 0x800
	s_mov_b32 m0, s13
	s_nop 0
	global_load_lds_dwordx4 v[52:53], off
	v_lshl_add_u64 v[50:51], v[50:51], 0, s[54:55]
	s_addk_i32 s12, 0xc00
	s_mov_b32 m0, s12
	s_nop 0
	global_load_lds_dwordx4 v[50:51], off
	s_add_u32 s40, s40, 0x80
	s_addc_u32 s41, s41, 0
; DI void st_bf4(u16* p, float a, float b, float c, float d) { *(uint2*)p = make_uint2(pk2(a, b), pk2(c, d)); }
; template <int MT, class Epi>
; DI void gemm_tile(const u16* __restrict__ X, long ldx, const u16* __restrict__ W, long ldw, int K, char* smem,
;                   int m0, int n0, const Epi& epi, bool pre = false, const u16* Xn = nullptr, const u16* Wn = nullptr) {
;     ...
;   do {
;     asm volatile("s_waitcnt vmcnt(0)" ::: "memory");
;     __syncthreads();
;     if (kt + 1 < nk) GT_DMA((unsigned)((kt + 1) & 1) * 32768u)
;     else if (Xn != nullptr) { xe = Xn + oxe; xo = Xn + oxo; we = Wn + owe; wo = Wn + owo; GT_DMA(0u) }
;     const char* cur = smem + (kt & 1) * 32768;
; #pragma unroll
;     for (int ks = 0; ks < 2; ++ks) {
;       bf16x8 xf[MT], wf[4];
;       const int ch = ((ks * 4 + g) ^ rsw) << 4;
; #pragma unroll
;       for (int i = 0; i < MT; ++i) xf[i] = *(const bf16x8*)(cur + (wm * 16 * MT + i * 16 + lr) * 128 + ch);
; #pragma unroll
;       for (int i = 0; i < 4; ++i) wf[i] = *(const bf16x8*)(cur + 16384 + (wn * 64 + i * 16 + lr) * 128 + ch);
; #pragma unroll
;       for (int nt = 0; nt < 4; ++nt)
; #pragma unroll
;         for (int mt = 0; mt < MT; ++mt)
;           acc[nt][mt] = __builtin_amdgcn_mfma_f32_16x16x32_bf16(wf[nt], xf[mt], acc[nt][mt], 0, 0, 0);
;     }
;   } while (++kt < nk);
;     ...
;   epi.run(acc, m0 + wm * 16 * MT + lr, n0 + wn * 64 + 4 * g);
;   template <int NT, int MT> DI void run(f32x4 (&acc)[NT][MT], int mb, int nb) const {
; #pragma unroll
;     for (int nt = 0; nt < NT; ++nt)
; #pragma unroll
;       for (int mt = 0; mt < MT; ++mt) {
;         f32x4 v = acc[nt][mt];
;         st_bf4(C + (size_t)(mb + mt * 16) * ldc + nb + nt * 16, v[0], v[1], v[2], v[3]);
;       }
;   }
.LBB0_28:
	s_add_i32 s12, s10, 0xc000
	s_add_i32 s11, s12, 0xfffee000
	s_cmp_lt_u32 s12, 0x12000
	s_cselect_b32 s12, s12, s11
	s_add_i32 s11, s10, 0x6000
	s_cmp_eq_u32 s11, 0x12000
	s_cselect_b32 s11, 0, s11
	v_lshl_add_u64 v[54:55], v[36:37], 0, s[40:41]
	v_lshl_add_u64 v[56:57], v[38:39], 0, s[40:41]
	s_waitcnt vmcnt(6)
	s_barrier
	s_cmp_eq_u32 s40, 0x780
	s_cbranch_scc1 .Lst3_skip_0
	s_add_i32 s13, s12, s8
	s_mov_b32 m0, s13
	s_nop 0
	global_load_lds_dwordx4 v[56:57], off
	v_lshl_add_u64 v[52:53], v[34:35], 0, s[40:41]
	v_lshl_add_u64 v[54:55], v[54:55], 0, s[94:95]
	s_addk_i32 s13, 0x400
	s_mov_b32 m0, s13
	s_nop 0
	global_load_lds_dwordx4 v[54:55], off
	v_lshl_add_u64 v[50:51], v[32:33], 0, s[40:41]
	v_lshl_add_u64 v[58:59], v[52:53], 0, s[16:17]
	s_add_i32 s12, s12, s9
	s_mov_b32 m0, s12
	s_nop 0
	global_load_lds_dwordx4 v[58:59], off
	v_lshl_add_u64 v[54:55], v[50:51], 0, s[94:95]
	s_add_i32 s13, s12, 0x400
	s_mov_b32 m0, s13
	s_nop 0
	global_load_lds_dwordx4 v[54:55], off
	v_lshl_add_u64 v[52:53], v[52:53], 0, s[66:67]
	s_add_i32 s13, s12, 0x800
	s_mov_b32 m0, s13
	s_nop 0
	global_load_lds_dwordx4 v[52:53], off
	v_lshl_add_u64 v[50:51], v[50:51], 0, s[54:55]
	s_addk_i32 s12, 0xc00
	s_mov_b32 m0, s12
	s_nop 0
	global_load_lds_dwordx4 v[50:51], off
.Lst3_skip_0:
	v_or_b32_e32 v49, s10, v48
	v_add3_u32 v54, v49, v47, v44
	v_add3_u32 v49, v49, v45, v44
	ds_read_b128 v[50:53], v54
	ds_read_b128 v[54:57], v54 offset:2048
	ds_read_b128 v[58:61], v49 offset:8192
	ds_read_b128 v[62:65], v49 offset:10240
	ds_read_b128 v[66:69], v49 offset:12288
	ds_read_b128 v[70:73], v49 offset:14336
	v_or_b32_e32 v49, s10, v46
	s_waitcnt lgkmcnt(3)
	v_mfma_f32_16x16x32_bf16 v[24:27], v[58:61], v[54:57], v[24:27]
	s_add_u32 s40, s40, 0x80
	s_addc_u32 s41, s41, 0
	s_cmpk_lg_i32 s40, 0x800
	s_waitcnt lgkmcnt(2)
	v_mfma_f32_16x16x32_bf16 v[16:19], v[62:65], v[54:57], v[16:19]
	s_mov_b32 s10, s11
	s_waitcnt lgkmcnt(1)
	v_mfma_f32_16x16x32_bf16 v[8:11], v[66:69], v[54:57], v[8:11]
	s_waitcnt lgkmcnt(0)
	v_mfma_f32_16x16x32_bf16 v[0:3], v[70:73], v[54:57], v[0:3]
	v_add3_u32 v54, v49, v47, v44
	v_add3_u32 v49, v49, v45, v44
	v_mfma_f32_16x16x32_bf16 v[28:31], v[58:61], v[50:53], v[28:31]
	v_mfma_f32_16x16x32_bf16 v[20:23], v[62:65], v[50:53], v[20:23]
	v_mfma_f32_16x16x32_bf16 v[12:15], v[66:69], v[50:53], v[12:15]
	v_mfma_f32_16x16x32_bf16 v[4:7], v[70:73], v[50:53], v[4:7]
	ds_read_b128 v[50:53], v54
	ds_read_b128 v[54:57], v54 offset:2048
	ds_read_b128 v[58:61], v49 offset:8192
	ds_read_b128 v[62:65], v49 offset:10240
	ds_read_b128 v[66:69], v49 offset:12288
	ds_read_b128 v[70:73], v49 offset:14336
	s_waitcnt lgkmcnt(3)
	v_mfma_f32_16x16x32_bf16 v[28:31], v[58:61], v[50:53], v[28:31]
	v_mfma_f32_16x16x32_bf16 v[24:27], v[58:61], v[54:57], v[24:27]
	s_waitcnt lgkmcnt(2)
	v_mfma_f32_16x16x32_bf16 v[20:23], v[62:65], v[50:53], v[20:23]
	v_mfma_f32_16x16x32_bf16 v[16:19], v[62:65], v[54:57], v[16:19]
	s_waitcnt lgkmcnt(1)
	v_mfma_f32_16x16x32_bf16 v[12:15], v[66:69], v[50:53], v[12:15]
	v_mfma_f32_16x16x32_bf16 v[8:11], v[66:69], v[54:57], v[8:11]
	s_waitcnt lgkmcnt(0)
	v_mfma_f32_16x16x32_bf16 v[4:7], v[70:73], v[50:53], v[4:7]
	v_mfma_f32_16x16x32_bf16 v[0:3], v[70:73], v[54:57], v[0:3]
	s_cbranch_scc1 .LBB0_28
	v_add3_u32 v36, v48, v47, v44
	v_add3_u32 v60, v48, v45, v44
	s_waitcnt vmcnt(0)
	s_barrier
	ds_read_b128 v[32:35], v36 offset:0
	ds_read_b128 v[36:39], v36 offset:2048
	ds_read_b128 v[48:51], v60 offset:8192
	ds_read_b128 v[52:55], v60 offset:10240
	ds_read_b128 v[56:59], v60 offset:12288
	ds_read_b128 v[60:63], v60 offset:14336
	s_waitcnt lgkmcnt(3)
	v_mfma_f32_16x16x32_bf16 v[24:27], v[48:51], v[36:39], v[24:27]
	s_lshl_b32 s7, s7, 7
	s_waitcnt lgkmcnt(2)
	v_mfma_f32_16x16x32_bf16 v[16:19], v[52:55], v[36:39], v[16:19]
	s_waitcnt lgkmcnt(1)
	v_mfma_f32_16x16x32_bf16 v[12:15], v[56:59], v[32:35], v[12:15]
	v_mfma_f32_16x16x32_bf16 v[8:11], v[56:59], v[36:39], v[8:11]
	v_add3_u32 v56, v46, v45, v44
	s_waitcnt lgkmcnt(0)
	v_mfma_f32_16x16x32_bf16 v[0:3], v[60:63], v[36:39], v[0:3]
	v_add3_u32 v36, v46, v47, v44
	v_mfma_f32_16x16x32_bf16 v[28:31], v[48:51], v[32:35], v[28:31]
	v_mfma_f32_16x16x32_bf16 v[20:23], v[52:55], v[32:35], v[20:23]
	v_mfma_f32_16x16x32_bf16 v[4:7], v[60:63], v[32:35], v[4:7]
	ds_read_b128 v[32:35], v36 offset:0
	ds_read_b128 v[36:39], v36 offset:2048
	ds_read_b128 v[44:47], v56 offset:8192
	ds_read_b128 v[48:51], v56 offset:10240
	ds_read_b128 v[52:55], v56 offset:12288
	ds_read_b128 v[56:59], v56 offset:14336
	s_waitcnt lgkmcnt(3)
	v_mfma_f32_16x16x32_bf16 v[28:31], v[44:47], v[32:35], v[28:31]
	s_waitcnt lgkmcnt(2)
	v_mfma_f32_16x16x32_bf16 v[20:23], v[48:51], v[32:35], v[20:23]
	s_nop 5
	v_cvt_pk_bf16_f32 v28, v28, v29
	v_cvt_pk_bf16_f32 v29, v30, v31
	s_waitcnt lgkmcnt(1)
	v_mfma_f32_16x16x32_bf16 v[12:15], v[52:55], v[32:35], v[12:15]
	s_waitcnt lgkmcnt(0)
	v_mfma_f32_16x16x32_bf16 v[4:7], v[56:59], v[32:35], v[4:7]
	v_lshlrev_b32_e32 v32, 5, v40
	v_or3_b32 v182, v32, s38, v41
	v_lshl_add_u32 v32, v43, 6, s7
	v_lshl_or_b32 v32, v42, 2, v32
	v_ashrrev_i32_e32 v33, 31, v32
	v_lshlrev_b64 v[34:35], 11, v[182:183]
	v_mfma_f32_16x16x32_bf16 v[24:27], v[44:47], v[36:39], v[24:27]
	v_lshl_add_u64 v[34:35], s[92:93], 0, v[34:35]
	v_lshlrev_b64 v[32:33], 1, v[32:33]
	v_lshl_add_u64 v[34:35], v[34:35], 0, v[32:33]
	v_mfma_f32_16x16x32_bf16 v[16:19], v[48:51], v[36:39], v[16:19]
	v_or_b32_e32 v182, 16, v182
	global_store_dwordx2 v[34:35], v[28:29], off
	v_lshlrev_b64 v[28:29], 11, v[182:183]
	v_mfma_f32_16x16x32_bf16 v[8:11], v[52:55], v[36:39], v[8:11]
	v_lshl_add_u64 v[28:29], s[92:93], 0, v[28:29]
	v_lshl_add_u64 v[28:29], v[28:29], 0, v[32:33]
	v_cvt_pk_bf16_f32 v24, v24, v25
	v_mfma_f32_16x16x32_bf16 v[0:3], v[56:59], v[36:39], v[0:3]
	v_cvt_pk_bf16_f32 v25, v26, v27
	v_cvt_pk_bf16_f32 v20, v20, v21
	v_cvt_pk_bf16_f32 v21, v22, v23
	v_cvt_pk_bf16_f32 v16, v16, v17
	v_cvt_pk_bf16_f32 v17, v18, v19
	v_cvt_pk_bf16_f32 v12, v12, v13
	v_cvt_pk_bf16_f32 v13, v14, v15
	v_cvt_pk_bf16_f32 v8, v8, v9
	v_cvt_pk_bf16_f32 v9, v10, v11
	v_cvt_pk_bf16_f32 v4, v4, v5
	v_cvt_pk_bf16_f32 v5, v6, v7
	v_cvt_pk_bf16_f32 v0, v0, v1
	v_cvt_pk_bf16_f32 v1, v2, v3
	s_mov_b64 s[38:39], 0
	global_store_dwordx2 v[28:29], v[24:25], off
	global_store_dwordx2 v[34:35], v[20:21], off offset:32
	global_store_dwordx2 v[28:29], v[16:17], off offset:32
	global_store_dwordx2 v[34:35], v[12:13], off offset:64
	global_store_dwordx2 v[28:29], v[8:9], off offset:64
	global_store_dwordx2 v[34:35], v[4:5], off offset:96
	global_store_dwordx2 v[28:29], v[0:1], off offset:96

; template <int MT, class Epi>
; DI void gemm_tile(const u16* __restrict__ X, long ldx, const u16* __restrict__ W, long ldw, int K, char* smem,
;                   int m0, int n0, const Epi& epi, bool pre = false, const u16* Xn = nullptr, const u16* Wn = nullptr) {
;     ...
;   const int r8 = lane >> 3, c0 = (lane & 7) ^ (r8 >> 1);
;   const long oxe = (long)(wu * MT * 8 + r8) * ldx + (c0 << 3), oxo = (long)(wu * MT * 8 + r8) * ldx + ((c0 ^ 4) << 3);
;   const long owe = (long)(wu * 32 + r8) * ldw + (c0 << 3), owo = (long)(wu * 32 + r8) * ldw + ((c0 ^ 4) << 3);
;   const u16 *xe = X + oxe, *xo = X + oxo, *we = W + owe, *wo = W + owo;
;   const long ldx8 = 8 * ldx, ldw8 = 8 * ldw;
;   const unsigned xdst = sbase + wu * MT * 1024, wdst = sbase + 16384 + wu * 4096;
;     ...
;   if (!pre) {
;     __syncthreads();
;     GT_DMA(0u)
;   } else {
;     xe += 64; xo += 64; we += 64; wo += 64;
;   }
;   const int nk = K >> 6;
;   int kt = 0;
;   do {
;     asm volatile("s_waitcnt vmcnt(0)" ::: "memory");
;     __syncthreads();
;     if (kt + 1 < nk) GT_DMA((unsigned)((kt + 1) & 1) * 32768u)
;     else if (Xn != nullptr) { xe = Xn + oxe; xo = Xn + oxo; we = Wn + owe; wo = Wn + owo; GT_DMA(0u) }
; DI void phase_even(const Params& p, int e, int sub, char* smem) {
;     ...
;         const int u = t - 512, tm = u >> 3, tn = u & 7, m0 = M_PROMPT + tm * 64;
;         gemm_tile<2>(gbuf + (size_t)m0 * 2048, 2048, W + WE_OUT + (size_t)tn * 128 * 2048, 2048, 2048, smem, m0, tn * 128, epi);
.LBB0_286:
	s_and_b32 s7, s4, 7
	s_lshl_b32 s34, s7, 19
	s_cmpk_gt_i32 s6, 0x1ff
	s_mov_b64 s[38:39], -1
	s_cbranch_scc0 .LBB0_290
	s_bfe_u32 s8, s5, 0x190006
	s_mov_b32 s9, s35
	s_lshl_b64 s[12:13], s[8:9], 18
	s_lshl_b32 s8, s6, 3
	s_and_b32 s8, s8, 0x7fffffc0
	s_add_i32 s38, s8, 0x3000
	s_mov_b32 s39, s35
	s_and_b32 s7, s6, 7
	s_lshl_b64 s[8:9], s[38:39], 12
	v_readlane_b32 s10, v252, 35
	v_mov_b32_e32 v3, v185
	v_readlane_b32 s11, v252, 36
	s_add_u32 s8, s10, s8
	s_addc_u32 s9, s11, s9
	v_ashrrev_i32_e32 v4, 6, v3
	v_bfe_u32 v6, v3, 3, 3
	v_readfirstlane_b32 s11, v4
	v_and_b32_e32 v1, 1, v4
	v_bfe_u32 v43, v3, 4, 2
	v_lshl_or_b32 v4, s11, 4, v6
	v_bitop3_b32 v10, v43, v3, 7 bitop3:0x78
	v_ashrrev_i32_e32 v5, 31, v4
	s_lshl_b32 s10, s7, 19
	v_readlane_b32 s16, v252, 39
	v_lshl_or_b32 v6, s11, 5, v6
	v_lshlrev_b64 v[4:5], 12, v[4:5]
	v_lshlrev_b32_e32 v182, 4, v10
	v_readlane_b32 s17, v252, 40
	s_add_u32 s14, s16, s10
	v_mov_b32_e32 v2, v183
	v_ashrrev_i32_e32 v7, 31, v6
	v_lshl_add_u64 v[8:9], s[8:9], 0, v[4:5]
	v_xor_b32_e32 v12, 64, v182
	v_mov_b32_e32 v13, v183
	s_addc_u32 s15, s17, 0
	v_lshl_add_u64 v[10:11], v[8:9], 0, v[182:183]
	v_lshl_add_u64 v[8:9], v[8:9], 0, v[12:13]
	v_lshlrev_b64 v[6:7], 12, v[6:7]
	s_lshl_b32 s8, s11, 11
	s_barrier
	s_mov_b32 m0, s8
	s_nop 0
	global_load_lds_dwordx4 v[10:11], off
	s_mov_b64 s[18:19], 0x8000
	v_lshl_add_u64 v[14:15], s[14:15], 0, v[6:7]
	s_lshl_b32 s11, s11, 12
	v_lshl_add_u64 v[8:9], v[8:9], 0, s[18:19]
	s_or_b32 s9, s8, 0x400
	s_mov_b32 m0, s9
	s_nop 0
	global_load_lds_dwordx4 v[8:9], off
	v_lshl_add_u64 v[16:17], v[14:15], 0, v[182:183]
	v_lshl_add_u64 v[8:9], v[14:15], 0, v[12:13]
	s_add_i32 s9, s11, 0x2000
	s_mov_b32 m0, s9
	s_nop 0
	global_load_lds_dwordx4 v[16:17], off
	v_lshl_add_u64 v[10:11], v[8:9], 0, s[18:19]
	s_add_i32 s14, s11, 0x2400
	s_mov_b32 m0, s14
	s_nop 0
	global_load_lds_dwordx4 v[10:11], off
	s_mov_b64 s[14:15], 0x10000
	v_lshl_add_u64 v[10:11], v[16:17], 0, s[14:15]
	s_add_i32 s14, s11, 0x2800
	s_mov_b32 m0, s14
	s_nop 0
	global_load_lds_dwordx4 v[10:11], off
	s_mov_b64 s[14:15], 0x18000
	v_lshrrev_b32_e32 v18, 1, v3
	v_lshl_add_u64 v[8:9], v[8:9], 0, s[14:15]
	s_addk_i32 s11, 0x2c00
	s_mov_b32 m0, s11
	s_nop 0
	global_load_lds_dwordx4 v[8:9], off
	v_bitop3_b32 v8, v43, v18, 7 bitop3:0x78
	v_lshl_add_u64 v[6:7], s[34:35], 0, v[6:7]
	v_lshlrev_b32_e32 v49, 4, v8
	v_lshl_add_u64 v[8:9], v[6:7], 0, v[12:13]
	v_lshl_add_u64 v[34:35], s[16:17], 0, v[8:9]
	v_readlane_b32 s16, v255, 5
	v_lshl_add_u64 v[6:7], v[6:7], 0, v[182:183]
	v_readlane_b32 s20, v255, 9
	v_readlane_b32 s21, v255, 10
	v_lshl_add_u64 v[4:5], s[12:13], 0, v[4:5]
	v_readlane_b32 s12, v254, 63
	v_lshl_add_u64 v[36:37], s[20:21], 0, v[6:7]
	v_bitop3_b32 v6, v4, v182, 64 bitop3:0xf6
	v_mov_b32_e32 v7, v5
	v_readlane_b32 s13, v255, 0
	v_and_b32_e32 v42, 15, v3
	v_ashrrev_i32_e32 v44, 7, v3
	v_bfe_u32 v3, v3, 1, 3
	v_lshl_add_u64 v[38:39], s[12:13], 0, v[6:7]
	v_readlane_b32 s12, v255, 1
	v_bitop3_b32 v3, v43, v3, 4 bitop3:0x36
	v_readlane_b32 s17, v255, 6
	v_readlane_b32 s18, v255, 7
	v_readlane_b32 s19, v255, 8
	v_or_b32_e32 v4, v4, v182
	v_readlane_b32 s13, v255, 2
	s_mov_b32 s10, 0
	v_lshlrev_b32_e32 v48, 12, v1
	v_lshlrev_b32_e32 v45, 7, v42
	v_lshlrev_b32_e32 v46, 13, v44
	v_lshlrev_b32_e32 v47, 4, v3
	v_lshl_add_u64 v[40:41], s[12:13], 0, v[4:5]
	s_mov_b64 s[40:41], 0
	v_mov_b32_e32 v3, v2
	v_mov_b32_e32 v4, v2
	v_mov_b32_e32 v5, v2
	v_mov_b32_e32 v6, v2
	v_mov_b32_e32 v7, v2
	v_mov_b32_e32 v8, v2
	v_mov_b32_e32 v9, v2
	v_mov_b32_e32 v10, v2
	v_mov_b32_e32 v11, v2
	v_mov_b32_e32 v12, v2
	v_mov_b32_e32 v13, v2
	v_mov_b32_e32 v14, v2
	v_mov_b32_e32 v15, v2
	v_mov_b32_e32 v16, v2
	v_mov_b32_e32 v17, v2
	v_mov_b32_e32 v18, v2
	v_mov_b32_e32 v19, v2
	v_mov_b32_e32 v20, v2
	v_mov_b32_e32 v21, v2
	v_mov_b32_e32 v22, v2
	v_mov_b32_e32 v23, v2
	v_mov_b32_e32 v24, v2
	v_mov_b32_e32 v25, v2
	v_mov_b32_e32 v26, v2
	v_mov_b32_e32 v27, v2
	v_mov_b32_e32 v28, v2
	v_mov_b32_e32 v29, v2
	v_mov_b32_e32 v30, v2
	v_mov_b32_e32 v31, v2
	v_mov_b32_e32 v32, v2
	v_mov_b32_e32 v33, v2
	s_mov_b64 s[16:17], 0xa00080
	s_mov_b64 s[18:19], 0xa10080
	s_mov_b64 s[20:21], 0x18080
	v_readlane_b32 s22, v255, 11
	v_readlane_b32 s23, v255, 12
	s_mov_b32 s12, 0x6000
	v_lshl_add_u64 v[54:55], v[38:39], 0, s[40:41]
	v_lshl_add_u64 v[56:57], v[40:41], 0, s[40:41]
	s_add_i32 s13, s12, s8
	s_mov_b32 m0, s13
	s_nop 0
	global_load_lds_dwordx4 v[56:57], off
	v_lshl_add_u64 v[52:53], v[36:37], 0, s[40:41]
	v_lshl_add_u64 v[54:55], v[54:55], 0, s[78:79]
	s_addk_i32 s13, 0x400
	s_mov_b32 m0, s13
	s_nop 0
	global_load_lds_dwordx4 v[54:55], off
	v_lshl_add_u64 v[50:51], v[34:35], 0, s[40:41]
	v_lshl_add_u64 v[58:59], v[52:53], 0, s[16:17]
	s_add_i32 s12, s12, s9
	s_mov_b32 m0, s12
	s_nop 0
	global_load_lds_dwordx4 v[58:59], off
	v_lshl_add_u64 v[54:55], v[50:51], 0, s[78:79]
	s_add_i32 s13, s12, 0x400
	s_mov_b32 m0, s13
	s_nop 0
	global_load_lds_dwordx4 v[54:55], off
	v_lshl_add_u64 v[52:53], v[52:53], 0, s[18:19]
	s_add_i32 s13, s12, 0x800
	s_mov_b32 m0, s13
	s_nop 0
	global_load_lds_dwordx4 v[52:53], off
	v_lshl_add_u64 v[50:51], v[50:51], 0, s[20:21]
	s_addk_i32 s12, 0xc00
	s_mov_b32 m0, s12
	s_nop 0
	global_load_lds_dwordx4 v[50:51], off
	s_add_u32 s40, s40, 0x80
	s_addc_u32 s41, s41, 0
; DI void st_bf4(u16* p, float a, float b, float c, float d) { *(uint2*)p = make_uint2(pk2(a, b), pk2(c, d)); }
; template <int MT, class Epi>
; DI void gemm_tile(const u16* __restrict__ X, long ldx, const u16* __restrict__ W, long ldw, int K, char* smem,
;                   int m0, int n0, const Epi& epi, bool pre = false, const u16* Xn = nullptr, const u16* Wn = nullptr) {
;     ...
;   do {
;     asm volatile("s_waitcnt vmcnt(0)" ::: "memory");
;     __syncthreads();
;     if (kt + 1 < nk) GT_DMA((unsigned)((kt + 1) & 1) * 32768u)
;     else if (Xn != nullptr) { xe = Xn + oxe; xo = Xn + oxo; we = Wn + owe; wo = Wn + owo; GT_DMA(0u) }
;     const char* cur = smem + (kt & 1) * 32768;
; #pragma unroll
;     for (int ks = 0; ks < 2; ++ks) {
;       bf16x8 xf[MT], wf[4];
;       const int ch = ((ks * 4 + g) ^ rsw) << 4;
; #pragma unroll
;       for (int i = 0; i < MT; ++i) xf[i] = *(const bf16x8*)(cur + (wm * 16 * MT + i * 16 + lr) * 128 + ch);
; #pragma unroll
;       for (int i = 0; i < 4; ++i) wf[i] = *(const bf16x8*)(cur + 16384 + (wn * 64 + i * 16 + lr) * 128 + ch);
; #pragma unroll
;       for (int nt = 0; nt < 4; ++nt)
; #pragma unroll
;         for (int mt = 0; mt < MT; ++mt)
;           acc[nt][mt] = __builtin_amdgcn_mfma_f32_16x16x32_bf16(wf[nt], xf[mt], acc[nt][mt], 0, 0, 0);
;     }
;   } while (++kt < nk);
;     ...
;   epi.run(acc, m0 + wm * 16 * MT + lr, n0 + wn * 64 + 4 * g);
;   template <int NT, int MT> DI void run(f32x4 (&acc)[NT][MT], int mb, int nb) const {
; #pragma unroll
;     for (int nt = 0; nt < NT; ++nt)
; #pragma unroll
;       for (int mt = 0; mt < MT; ++mt) {
;         f32x4 v = acc[nt][mt];
;         st_bf4(C + (size_t)(mb + mt * 16) * ldc + nb + nt * 16, v[0], v[1], v[2], v[3]);
;       }
.LBB0_288:
	s_add_i32 s12, s10, 0xc000
	s_add_i32 s11, s12, 0xfffee000
	s_cmp_lt_u32 s12, 0x12000
	s_cselect_b32 s12, s12, s11
	s_add_i32 s11, s10, 0x6000
	s_cmp_eq_u32 s11, 0x12000
	s_cselect_b32 s11, 0, s11
	v_lshl_add_u64 v[54:55], v[38:39], 0, s[40:41]
	v_lshl_add_u64 v[56:57], v[40:41], 0, s[40:41]
	s_waitcnt vmcnt(6)
	s_barrier
	s_cmp_eq_u32 s40, 0xf80
	s_cbranch_scc1 .Lst3_skip_1
	s_add_i32 s13, s12, s8
	s_mov_b32 m0, s13
	s_nop 0
	global_load_lds_dwordx4 v[56:57], off
	v_lshl_add_u64 v[52:53], v[36:37], 0, s[40:41]
	v_lshl_add_u64 v[54:55], v[54:55], 0, s[78:79]
	s_addk_i32 s13, 0x400
	s_mov_b32 m0, s13
	s_nop 0
	global_load_lds_dwordx4 v[54:55], off
	v_lshl_add_u64 v[50:51], v[34:35], 0, s[40:41]
	v_lshl_add_u64 v[58:59], v[52:53], 0, s[16:17]
	s_add_i32 s12, s12, s9
	s_mov_b32 m0, s12
	s_nop 0
	global_load_lds_dwordx4 v[58:59], off
	v_lshl_add_u64 v[54:55], v[50:51], 0, s[78:79]
	s_add_i32 s13, s12, 0x400
	s_mov_b32 m0, s13
	s_nop 0
	global_load_lds_dwordx4 v[54:55], off
	v_lshl_add_u64 v[52:53], v[52:53], 0, s[18:19]
	s_add_i32 s13, s12, 0x800
	s_mov_b32 m0, s13
	s_nop 0
	global_load_lds_dwordx4 v[52:53], off
	v_lshl_add_u64 v[50:51], v[50:51], 0, s[20:21]
	s_addk_i32 s12, 0xc00
	s_mov_b32 m0, s12
	s_nop 0
	global_load_lds_dwordx4 v[50:51], off
.Lst3_skip_1:
	v_or_b32_e32 v58, s10, v49
	v_add3_u32 v54, v58, v48, v45
	ds_read_b128 v[50:53], v54
	ds_read_b128 v[54:57], v54 offset:2048
	v_add3_u32 v70, v58, v46, v45
	ds_read_b128 v[58:61], v70 offset:8192
	ds_read_b128 v[62:65], v70 offset:10240
	ds_read_b128 v[66:69], v70 offset:12288
	ds_read_b128 v[70:73], v70 offset:14336
	s_waitcnt lgkmcnt(3)
	v_mfma_f32_16x16x32_bf16 v[30:33], v[58:61], v[50:53], v[30:33]
	s_add_u32 s40, s40, 0x80
	s_addc_u32 s41, s41, 0
	s_cmpk_lg_i32 s40, 0x1000
	v_mfma_f32_16x16x32_bf16 v[26:29], v[58:61], v[54:57], v[26:29]
	v_or_b32_e32 v58, s10, v47
	s_mov_b32 s10, s11
	s_waitcnt lgkmcnt(2)
	v_mfma_f32_16x16x32_bf16 v[18:21], v[62:65], v[54:57], v[18:21]
	s_waitcnt lgkmcnt(1)
	v_mfma_f32_16x16x32_bf16 v[10:13], v[66:69], v[54:57], v[10:13]
	s_waitcnt lgkmcnt(0)
	v_mfma_f32_16x16x32_bf16 v[6:9], v[70:73], v[50:53], v[6:9]
	v_mfma_f32_16x16x32_bf16 v[2:5], v[70:73], v[54:57], v[2:5]
	v_add3_u32 v54, v58, v48, v45
	v_add3_u32 v70, v58, v46, v45
	v_mfma_f32_16x16x32_bf16 v[22:25], v[62:65], v[50:53], v[22:25]
	v_mfma_f32_16x16x32_bf16 v[14:17], v[66:69], v[50:53], v[14:17]
	ds_read_b128 v[50:53], v54
	ds_read_b128 v[54:57], v54 offset:2048
	ds_read_b128 v[58:61], v70 offset:8192
	ds_read_b128 v[62:65], v70 offset:10240
	ds_read_b128 v[66:69], v70 offset:12288
	ds_read_b128 v[70:73], v70 offset:14336
	s_waitcnt lgkmcnt(3)
	v_mfma_f32_16x16x32_bf16 v[30:33], v[58:61], v[50:53], v[30:33]
	v_mfma_f32_16x16x32_bf16 v[26:29], v[58:61], v[54:57], v[26:29]
	s_waitcnt lgkmcnt(2)
	v_mfma_f32_16x16x32_bf16 v[22:25], v[62:65], v[50:53], v[22:25]
	v_mfma_f32_16x16x32_bf16 v[18:21], v[62:65], v[54:57], v[18:21]
	s_waitcnt lgkmcnt(1)
	v_mfma_f32_16x16x32_bf16 v[14:17], v[66:69], v[50:53], v[14:17]
	v_mfma_f32_16x16x32_bf16 v[10:13], v[66:69], v[54:57], v[10:13]
	s_waitcnt lgkmcnt(0)
	v_mfma_f32_16x16x32_bf16 v[6:9], v[70:73], v[50:53], v[6:9]
	v_mfma_f32_16x16x32_bf16 v[2:5], v[70:73], v[54:57], v[2:5]
	s_cbranch_scc1 .LBB0_288
	v_add3_u32 v38, v49, v48, v45
	v_add3_u32 v49, v49, v46, v45
	s_waitcnt vmcnt(0)
	s_barrier
	ds_read_b128 v[34:37], v38 offset:24576
	ds_read_b128 v[38:41], v38 offset:26624
	ds_read_b128 v[50:53], v49 offset:32768
	ds_read_b128 v[54:57], v49 offset:34816
	ds_read_b128 v[58:61], v49 offset:36864
	ds_read_b128 v[62:65], v49 offset:38912
	s_waitcnt lgkmcnt(3)
	v_mfma_f32_16x16x32_bf16 v[26:29], v[50:53], v[38:41], v[26:29]
	s_lshl_b32 s7, s7, 7
	v_lshlrev_b32_e32 v1, 5, v1
	v_or3_b32 v182, v1, s38, v42
	s_waitcnt lgkmcnt(2)
	v_mfma_f32_16x16x32_bf16 v[18:21], v[54:57], v[38:41], v[18:21]
	v_lshl_add_u32 v1, v44, 6, s7
	v_readlane_b32 s8, v252, 33
	v_readlane_b32 s9, v252, 34
	s_waitcnt lgkmcnt(1)
	v_mfma_f32_16x16x32_bf16 v[10:13], v[58:61], v[38:41], v[10:13]
	s_mov_b64 s[38:39], 0
	s_waitcnt lgkmcnt(0)
	v_mfma_f32_16x16x32_bf16 v[2:5], v[62:65], v[38:41], v[2:5]
	v_add3_u32 v38, v47, v48, v45
	v_add3_u32 v45, v47, v46, v45
	v_mfma_f32_16x16x32_bf16 v[30:33], v[50:53], v[34:37], v[30:33]
	v_mfma_f32_16x16x32_bf16 v[22:25], v[54:57], v[34:37], v[22:25]
	v_mfma_f32_16x16x32_bf16 v[14:17], v[58:61], v[34:37], v[14:17]
	v_mfma_f32_16x16x32_bf16 v[6:9], v[62:65], v[34:37], v[6:9]
	ds_read_b128 v[34:37], v38 offset:24576
	ds_read_b128 v[38:41], v38 offset:26624
	ds_read_b128 v[46:49], v45 offset:32768
	ds_read_b128 v[50:53], v45 offset:34816
	ds_read_b128 v[54:57], v45 offset:36864
	ds_read_b128 v[58:61], v45 offset:38912
	s_waitcnt lgkmcnt(3)
	v_mfma_f32_16x16x32_bf16 v[30:33], v[46:49], v[34:37], v[30:33]
	s_waitcnt lgkmcnt(2)
	v_mfma_f32_16x16x32_bf16 v[22:25], v[50:53], v[34:37], v[22:25]
	s_nop 5
	v_cvt_pk_bf16_f32 v30, v30, v31
	v_cvt_pk_bf16_f32 v31, v32, v33
	s_waitcnt lgkmcnt(1)
	v_mfma_f32_16x16x32_bf16 v[14:17], v[54:57], v[34:37], v[14:17]
	s_waitcnt lgkmcnt(0)
	v_mfma_f32_16x16x32_bf16 v[6:9], v[58:61], v[34:37], v[6:9]
	v_lshl_or_b32 v34, v43, 2, v1
	v_ashrrev_i32_e32 v35, 31, v34
	v_lshlrev_b64 v[36:37], 11, v[182:183]
	v_mfma_f32_16x16x32_bf16 v[26:29], v[46:49], v[38:41], v[26:29]
	v_lshl_add_u64 v[36:37], s[8:9], 0, v[36:37]
	v_lshlrev_b64 v[34:35], 1, v[34:35]
	v_lshl_add_u64 v[36:37], v[36:37], 0, v[34:35]
	v_mfma_f32_16x16x32_bf16 v[18:21], v[50:53], v[38:41], v[18:21]
	v_or_b32_e32 v182, 16, v182
	global_store_dwordx2 v[36:37], v[30:31], off
	v_lshlrev_b64 v[30:31], 11, v[182:183]
	v_mfma_f32_16x16x32_bf16 v[10:13], v[54:57], v[38:41], v[10:13]
	v_lshl_add_u64 v[30:31], s[8:9], 0, v[30:31]
	v_lshl_add_u64 v[30:31], v[30:31], 0, v[34:35]
	v_cvt_pk_bf16_f32 v26, v26, v27
	v_mfma_f32_16x16x32_bf16 v[2:5], v[58:61], v[38:41], v[2:5]
	v_cvt_pk_bf16_f32 v27, v28, v29
	v_cvt_pk_bf16_f32 v22, v22, v23
	v_cvt_pk_bf16_f32 v23, v24, v25
	v_cvt_pk_bf16_f32 v18, v18, v19
	v_cvt_pk_bf16_f32 v19, v20, v21
	v_cvt_pk_bf16_f32 v14, v14, v15
	v_cvt_pk_bf16_f32 v15, v16, v17
	v_cvt_pk_bf16_f32 v10, v10, v11
	v_cvt_pk_bf16_f32 v11, v12, v13
	v_cvt_pk_bf16_f32 v6, v6, v7
	v_cvt_pk_bf16_f32 v7, v8, v9
	v_cvt_pk_bf16_f32 v2, v2, v3
	v_cvt_pk_bf16_f32 v3, v4, v5
	global_store_dwordx2 v[30:31], v[26:27], off
	global_store_dwordx2 v[36:37], v[22:23], off offset:32
	global_store_dwordx2 v[30:31], v[18:19], off offset:32
	global_store_dwordx2 v[36:37], v[14:15], off offset:64
	global_store_dwordx2 v[30:31], v[10:11], off offset:64
	global_store_dwordx2 v[36:37], v[6:7], off offset:96
	global_store_dwordx2 v[30:31], v[2:3], off offset:96

; template <int MT, class Epi>
; DI void gemm_tile(const u16* __restrict__ X, long ldx, const u16* __restrict__ W, long ldw, int K, char* smem,
;                   int m0, int n0, const Epi& epi, bool pre = false, const u16* Xn = nullptr, const u16* Wn = nullptr) {
;     ...
;   const int r8 = lane >> 3, c0 = (lane & 7) ^ (r8 >> 1);
;   const long oxe = (long)(wu * MT * 8 + r8) * ldx + (c0 << 3), oxo = (long)(wu * MT * 8 + r8) * ldx + ((c0 ^ 4) << 3);
;   const long owe = (long)(wu * 32 + r8) * ldw + (c0 << 3), owo = (long)(wu * 32 + r8) * ldw + ((c0 ^ 4) << 3);
;   const u16 *xe = X + oxe, *xo = X + oxo, *we = W + owe, *wo = W + owo;
;   const long ldx8 = 8 * ldx, ldw8 = 8 * ldw;
;   const unsigned xdst = sbase + wu * MT * 1024, wdst = sbase + 16384 + wu * 4096;
;     ...
;   if (!pre) {
;     __syncthreads();
;     GT_DMA(0u)
;   } else {
;     xe += 64; xo += 64; we += 64; wo += 64;
;   }
;   const int nk = K >> 6;
;   int kt = 0;
;   do {
;     asm volatile("s_waitcnt vmcnt(0)" ::: "memory");
;     __syncthreads();
;     if (kt + 1 < nk) GT_DMA((unsigned)((kt + 1) & 1) * 32768u)
;     else if (Xn != nullptr) { xe = Xn + oxe; xo = Xn + oxo; we = Wn + owe; wo = Wn + owo; GT_DMA(0u) }
; DI void phase_odd(const Params& p, int o, int sub, char* smem) {
;     ...
;         const int u = t - 512, tm = u >> 3, tn = u & 7, m0 = M_PROMPT + tm * 64;
;         gemm_tile<2>(ao + (size_t)m0 * 1024, 1024, W + WO_O + (size_t)tn * 128 * 1024, 1024, 1024, smem, m0, tn * 128, epi);
.LBB0_904:
	s_and_b32 s7, s4, 7
	s_lshl_b32 s34, s7, 18
	s_cmpk_gt_i32 s6, 0x1ff
	s_mov_b64 s[38:39], -1
	s_cbranch_scc0 .LBB0_908
	s_bfe_u32 s8, s5, 0x190006
	s_mov_b32 s9, s35
	s_lshl_b64 s[12:13], s[8:9], 17
	s_lshl_b32 s8, s6, 3
	s_and_b32 s8, s8, 0x7fffffc0
	s_add_i32 s38, s8, 0x3000
	s_mov_b32 s39, s35
	s_and_b32 s7, s6, 7
	s_lshl_b64 s[8:9], s[38:39], 11
	v_readlane_b32 s10, v252, 24
	v_mov_b32_e32 v1, v185
	v_readlane_b32 s11, v252, 25
	s_add_u32 s8, s10, s8
	s_addc_u32 s9, s11, s9
	v_ashrrev_i32_e32 v2, 6, v1
	v_bfe_u32 v4, v1, 3, 3
	v_readfirstlane_b32 s11, v2
	v_and_b32_e32 v40, 1, v2
	v_bfe_u32 v42, v1, 4, 2
	v_lshl_or_b32 v2, s11, 4, v4
	v_bitop3_b32 v8, v42, v1, 7 bitop3:0x78
	v_ashrrev_i32_e32 v3, 31, v2
	s_lshl_b32 s10, s7, 18
	v_readlane_b32 s16, v252, 26
	v_lshl_or_b32 v4, s11, 5, v4
	v_lshlrev_b64 v[2:3], 11, v[2:3]
	v_lshlrev_b32_e32 v182, 4, v8
	v_readlane_b32 s17, v252, 27
	s_add_u32 s14, s16, s10
	v_mov_b32_e32 v0, v183
	v_ashrrev_i32_e32 v5, 31, v4
	v_lshl_add_u64 v[6:7], s[8:9], 0, v[2:3]
	v_xor_b32_e32 v10, 64, v182
	v_mov_b32_e32 v11, v183
	s_addc_u32 s15, s17, 0
	v_lshl_add_u64 v[8:9], v[6:7], 0, v[182:183]
	v_lshl_add_u64 v[6:7], v[6:7], 0, v[10:11]
	v_lshlrev_b64 v[4:5], 11, v[4:5]
	s_lshl_b32 s8, s11, 11
	s_barrier
	s_mov_b32 m0, s8
	s_nop 0
	global_load_lds_dwordx4 v[8:9], off
	s_mov_b64 s[18:19], 0x4000
	v_lshl_add_u64 v[12:13], s[14:15], 0, v[4:5]
	s_lshl_b32 s11, s11, 12
	v_lshl_add_u64 v[6:7], v[6:7], 0, s[18:19]
	s_or_b32 s9, s8, 0x400
	s_mov_b32 m0, s9
	s_nop 0
	global_load_lds_dwordx4 v[6:7], off
	v_lshl_add_u64 v[14:15], v[12:13], 0, v[182:183]
	v_lshl_add_u64 v[6:7], v[12:13], 0, v[10:11]
	s_add_i32 s9, s11, 0x2000
	s_mov_b32 m0, s9
	s_nop 0
	global_load_lds_dwordx4 v[14:15], off
	v_lshl_add_u64 v[8:9], v[6:7], 0, s[18:19]
	s_add_i32 s14, s11, 0x2400
	s_mov_b32 m0, s14
	s_nop 0
	global_load_lds_dwordx4 v[8:9], off
	s_mov_b64 s[14:15], 0x8000
	v_lshl_add_u64 v[8:9], v[14:15], 0, s[14:15]
	s_add_i32 s14, s11, 0x2800
	s_mov_b32 m0, s14
	s_nop 0
	global_load_lds_dwordx4 v[8:9], off
	s_mov_b64 s[14:15], 0xc000
	v_lshrrev_b32_e32 v16, 1, v1
	v_lshl_add_u64 v[6:7], v[6:7], 0, s[14:15]
	s_addk_i32 s11, 0x2c00
	s_mov_b32 m0, s11
	s_nop 0
	global_load_lds_dwordx4 v[6:7], off
	v_bitop3_b32 v6, v42, v16, 7 bitop3:0x78
	v_lshl_add_u64 v[4:5], s[34:35], 0, v[4:5]
	v_lshlrev_b32_e32 v48, 4, v6
	v_lshl_add_u64 v[6:7], v[4:5], 0, v[10:11]
	v_lshl_add_u64 v[32:33], s[16:17], 0, v[6:7]
	v_readlane_b32 s16, v255, 5
	v_lshl_add_u64 v[4:5], v[4:5], 0, v[182:183]
	v_readlane_b32 s20, v255, 9
	v_readlane_b32 s21, v255, 10
	v_lshl_add_u64 v[2:3], s[12:13], 0, v[2:3]
	v_readlane_b32 s12, v254, 54
	v_lshl_add_u64 v[34:35], s[20:21], 0, v[4:5]
	v_bitop3_b32 v4, v2, v182, 64 bitop3:0xf6
	v_mov_b32_e32 v5, v3
	v_readlane_b32 s13, v254, 55
	v_and_b32_e32 v41, 15, v1
	v_ashrrev_i32_e32 v43, 7, v1
	v_bfe_u32 v1, v1, 1, 3
	v_lshl_add_u64 v[36:37], s[12:13], 0, v[4:5]
	v_readlane_b32 s12, v254, 57
	v_bitop3_b32 v1, v42, v1, 4 bitop3:0x36
	v_readlane_b32 s17, v255, 6
	v_or_b32_e32 v2, v2, v182
	v_readlane_b32 s13, v254, 58
	s_mov_b32 s10, 0
	v_lshlrev_b32_e32 v47, 12, v40
	v_lshlrev_b32_e32 v44, 7, v41
	v_lshlrev_b32_e32 v45, 13, v43
	v_lshlrev_b32_e32 v46, 4, v1
	v_lshl_add_u64 v[38:39], s[12:13], 0, v[2:3]
	s_mov_b64 s[40:41], 0
	v_mov_b32_e32 v1, v0
	v_mov_b32_e32 v2, v0
	v_mov_b32_e32 v3, v0
	v_mov_b32_e32 v4, v0
	v_mov_b32_e32 v5, v0
	v_mov_b32_e32 v6, v0
	v_mov_b32_e32 v7, v0
	v_mov_b32_e32 v8, v0
	v_mov_b32_e32 v9, v0
	v_mov_b32_e32 v10, v0
	v_mov_b32_e32 v11, v0
	v_mov_b32_e32 v12, v0
	v_mov_b32_e32 v13, v0
	v_mov_b32_e32 v14, v0
	v_mov_b32_e32 v15, v0
	v_mov_b32_e32 v16, v0
	v_mov_b32_e32 v17, v0
	v_mov_b32_e32 v18, v0
	v_mov_b32_e32 v19, v0
	v_mov_b32_e32 v20, v0
	v_mov_b32_e32 v21, v0
	v_mov_b32_e32 v22, v0
	v_mov_b32_e32 v23, v0
	v_mov_b32_e32 v24, v0
	v_mov_b32_e32 v25, v0
	v_mov_b32_e32 v26, v0
	v_mov_b32_e32 v27, v0
	v_mov_b32_e32 v28, v0
	v_mov_b32_e32 v29, v0
	v_mov_b32_e32 v30, v0
	v_mov_b32_e32 v31, v0
	s_mov_b64 s[16:17], 0x5a0080
	v_readlane_b32 s18, v255, 7
	v_readlane_b32 s19, v255, 8
	v_readlane_b32 s22, v255, 11
	v_readlane_b32 s23, v255, 12
	s_mov_b32 s12, 0x6000
	v_lshl_add_u64 v[54:55], v[36:37], 0, s[40:41]
	v_lshl_add_u64 v[56:57], v[38:39], 0, s[40:41]
	s_add_i32 s13, s12, s8
	s_mov_b32 m0, s13
	s_nop 0
	global_load_lds_dwordx4 v[56:57], off
	v_lshl_add_u64 v[52:53], v[34:35], 0, s[40:41]
	v_lshl_add_u64 v[54:55], v[54:55], 0, s[94:95]
	s_addk_i32 s13, 0x400
	s_mov_b32 m0, s13
	s_nop 0
	global_load_lds_dwordx4 v[54:55], off
	v_lshl_add_u64 v[50:51], v[32:33], 0, s[40:41]
	v_lshl_add_u64 v[58:59], v[52:53], 0, s[16:17]
	s_add_i32 s12, s12, s9
	s_mov_b32 m0, s12
	s_nop 0
	global_load_lds_dwordx4 v[58:59], off
	v_lshl_add_u64 v[54:55], v[50:51], 0, s[94:95]
	s_add_i32 s13, s12, 0x400
	s_mov_b32 m0, s13
	s_nop 0
	global_load_lds_dwordx4 v[54:55], off
	v_lshl_add_u64 v[52:53], v[52:53], 0, s[66:67]
	s_add_i32 s13, s12, 0x800
	s_mov_b32 m0, s13
	s_nop 0
	global_load_lds_dwordx4 v[52:53], off
	v_lshl_add_u64 v[50:51], v[50:51], 0, s[54:55]
	s_addk_i32 s12, 0xc00
	s_mov_b32 m0, s12
	s_nop 0
	global_load_lds_dwordx4 v[50:51], off
	s_add_u32 s40, s40, 0x80
	s_addc_u32 s41, s41, 0

; template <int MT, class Epi>
; DI void gemm_tile(const u16* __restrict__ X, long ldx, const u16* __restrict__ W, long ldw, int K, char* smem,
;                   int m0, int n0, const Epi& epi, bool pre = false, const u16* Xn = nullptr, const u16* Wn = nullptr) {
;     ...
;   const int r8 = lane >> 3, c0 = (lane & 7) ^ (r8 >> 1);
;   const long oxe = (long)(wu * MT * 8 + r8) * ldx + (c0 << 3), oxo = (long)(wu * MT * 8 + r8) * ldx + ((c0 ^ 4) << 3);
;   const long owe = (long)(wu * 32 + r8) * ldw + (c0 << 3), owo = (long)(wu * 32 + r8) * ldw + ((c0 ^ 4) << 3);
;   const u16 *xe = X + oxe, *xo = X + oxo, *we = W + owe, *wo = W + owo;
;   const long ldx8 = 8 * ldx, ldw8 = 8 * ldw;
;   const unsigned xdst = sbase + wu * MT * 1024, wdst = sbase + 16384 + wu * 4096;
;     ...
;   if (!pre) {
;     __syncthreads();
;     GT_DMA(0u)
;   } else {
;     xe += 64; xo += 64; we += 64; wo += 64;
;   }
;   const int nk = K >> 6;
;   int kt = 0;
;   do {
;     asm volatile("s_waitcnt vmcnt(0)" ::: "memory");
;     __syncthreads();
;     if (kt + 1 < nk) GT_DMA((unsigned)((kt + 1) & 1) * 32768u)
;     else if (Xn != nullptr) { xe = Xn + oxe; xo = Xn + oxo; we = Wn + owe; wo = Wn + owo; GT_DMA(0u) }
; DI void phase_even(const Params& p, int e, int sub, char* smem) {
;     ...
;         const int u = t - 512, tm = u >> 3, tn = u & 7, m0 = M_PROMPT + tm * 64;
;         gemm_tile<2>(gbuf + (size_t)m0 * 2048, 2048, W + WE_OUT + (size_t)tn * 128 * 2048, 2048, 2048, smem, m0, tn * 128, epi);
.LBB0_1133:
	s_and_b32 s7, s4, 7
	s_lshl_b32 s34, s7, 19
	s_cmpk_gt_i32 s6, 0x1ff
	s_mov_b64 s[40:41], -1
	s_cbranch_scc0 .LBB0_1137
	s_bfe_u32 s8, s5, 0x190006
	s_mov_b32 s9, s35
	s_lshl_b64 s[12:13], s[8:9], 18
	s_lshl_b32 s8, s6, 3
	s_and_b32 s8, s8, 0x7fffffc0
	s_add_i32 s40, s8, 0x3000
	s_mov_b32 s41, s35
	s_and_b32 s7, s6, 7
	s_lshl_b64 s[8:9], s[40:41], 12
	v_readlane_b32 s10, v252, 35
	v_mov_b32_e32 v1, v185
	v_readlane_b32 s11, v252, 36
	s_add_u32 s8, s10, s8
	s_addc_u32 s9, s11, s9
	v_ashrrev_i32_e32 v2, 6, v1
	v_bfe_u32 v4, v1, 3, 3
	v_readfirstlane_b32 s11, v2
	v_and_b32_e32 v40, 1, v2
	v_bfe_u32 v42, v1, 4, 2
	v_lshl_or_b32 v2, s11, 4, v4
	v_bitop3_b32 v8, v42, v1, 7 bitop3:0x78
	v_ashrrev_i32_e32 v3, 31, v2
	s_lshl_b32 s10, s7, 19
	v_readlane_b32 s16, v252, 39
	v_lshl_or_b32 v4, s11, 5, v4
	v_lshlrev_b64 v[2:3], 12, v[2:3]
	v_lshlrev_b32_e32 v182, 4, v8
	v_readlane_b32 s17, v252, 40
	s_add_u32 s14, s16, s10
	v_mov_b32_e32 v0, v183
	v_ashrrev_i32_e32 v5, 31, v4
	v_lshl_add_u64 v[6:7], s[8:9], 0, v[2:3]
	v_xor_b32_e32 v10, 64, v182
	v_mov_b32_e32 v11, v183
	s_addc_u32 s15, s17, 0
	v_lshl_add_u64 v[8:9], v[6:7], 0, v[182:183]
	v_lshl_add_u64 v[6:7], v[6:7], 0, v[10:11]
	v_lshlrev_b64 v[4:5], 12, v[4:5]
	s_lshl_b32 s8, s11, 11
	s_waitcnt lgkmcnt(0)
	s_barrier
	s_mov_b32 m0, s8
	s_nop 0
	global_load_lds_dwordx4 v[8:9], off
	v_lshl_add_u64 v[12:13], s[14:15], 0, v[4:5]
	s_lshl_b32 s11, s11, 12
	v_lshl_add_u64 v[6:7], v[6:7], 0, s[56:57]
	s_or_b32 s9, s8, 0x400
	s_mov_b32 m0, s9
	s_nop 0
	global_load_lds_dwordx4 v[6:7], off
	v_lshl_add_u64 v[14:15], v[12:13], 0, v[182:183]
	v_lshl_add_u64 v[6:7], v[12:13], 0, v[10:11]
	s_add_i32 s9, s11, 0x2000
	s_mov_b32 m0, s9
	s_nop 0
	global_load_lds_dwordx4 v[14:15], off
	v_lshl_add_u64 v[8:9], v[6:7], 0, s[56:57]
	s_add_i32 s14, s11, 0x2400
	s_mov_b32 m0, s14
	s_nop 0
	global_load_lds_dwordx4 v[8:9], off
	v_lshrrev_b32_e32 v16, 1, v1
	v_lshl_add_u64 v[8:9], v[14:15], 0, s[58:59]
	s_add_i32 s14, s11, 0x2800
	s_mov_b32 m0, s14
	s_nop 0
	global_load_lds_dwordx4 v[8:9], off
	v_lshl_add_u64 v[6:7], v[6:7], 0, s[60:61]
	s_addk_i32 s11, 0x2c00
	s_mov_b32 m0, s11
	s_nop 0
	global_load_lds_dwordx4 v[6:7], off
	v_bitop3_b32 v6, v42, v16, 7 bitop3:0x78
	v_lshl_add_u64 v[4:5], s[34:35], 0, v[4:5]
	v_lshlrev_b32_e32 v48, 4, v6
	v_lshl_add_u64 v[6:7], v[4:5], 0, v[10:11]
	v_lshl_add_u64 v[32:33], s[16:17], 0, v[6:7]
	v_readlane_b32 s16, v255, 5
	v_and_b32_e32 v41, 15, v1
	v_ashrrev_i32_e32 v43, 7, v1
	v_bfe_u32 v1, v1, 1, 3
	v_lshl_add_u64 v[4:5], v[4:5], 0, v[182:183]
	v_readlane_b32 s20, v255, 9
	v_readlane_b32 s21, v255, 10
	v_lshl_add_u64 v[2:3], s[12:13], 0, v[2:3]
	v_bitop3_b32 v1, v42, v1, 4 bitop3:0x36
	v_readlane_b32 s17, v255, 6
	v_readlane_b32 s18, v255, 7
	v_readlane_b32 s19, v255, 8
	v_lshl_add_u64 v[34:35], s[20:21], 0, v[4:5]
	v_bitop3_b32 v4, v2, v182, 64 bitop3:0xf6
	v_mov_b32_e32 v5, v3
	v_or_b32_e32 v2, v2, v182
	s_mov_b32 s10, 0
	v_lshlrev_b32_e32 v47, 12, v40
	v_lshlrev_b32_e32 v44, 7, v41
	v_lshlrev_b32_e32 v45, 13, v43
	v_lshlrev_b32_e32 v46, 4, v1
	v_lshl_add_u64 v[36:37], s[46:47], 0, v[4:5]
	v_lshl_add_u64 v[38:39], s[48:49], 0, v[2:3]
	s_mov_b64 s[42:43], 0
	v_mov_b32_e32 v1, v0
	v_mov_b32_e32 v2, v0
	v_mov_b32_e32 v3, v0
	v_mov_b32_e32 v4, v0
	v_mov_b32_e32 v5, v0
	v_mov_b32_e32 v6, v0
	v_mov_b32_e32 v7, v0
	v_mov_b32_e32 v8, v0
	v_mov_b32_e32 v9, v0
	v_mov_b32_e32 v10, v0
	v_mov_b32_e32 v11, v0
	v_mov_b32_e32 v12, v0
	v_mov_b32_e32 v13, v0
	v_mov_b32_e32 v14, v0
	v_mov_b32_e32 v15, v0
	v_mov_b32_e32 v16, v0
	v_mov_b32_e32 v17, v0
	v_mov_b32_e32 v18, v0
	v_mov_b32_e32 v19, v0
	v_mov_b32_e32 v20, v0
	v_mov_b32_e32 v21, v0
	v_mov_b32_e32 v22, v0
	v_mov_b32_e32 v23, v0
	v_mov_b32_e32 v24, v0
	v_mov_b32_e32 v25, v0
	v_mov_b32_e32 v26, v0
	v_mov_b32_e32 v27, v0
	v_mov_b32_e32 v28, v0
	v_mov_b32_e32 v29, v0
	v_mov_b32_e32 v30, v0
	v_mov_b32_e32 v31, v0
	s_mov_b64 s[16:17], 0xa00080
	s_mov_b64 s[18:19], 0x18080
	v_readlane_b32 s22, v255, 11
	v_readlane_b32 s23, v255, 12
	s_mov_b32 s12, 0x6000
	v_lshl_add_u64 v[54:55], v[36:37], 0, s[42:43]
	v_lshl_add_u64 v[56:57], v[38:39], 0, s[42:43]
	s_add_i32 s13, s12, s8
	s_mov_b32 m0, s13
	s_nop 0
	global_load_lds_dwordx4 v[56:57], off
	v_lshl_add_u64 v[52:53], v[34:35], 0, s[42:43]
	v_lshl_add_u64 v[54:55], v[54:55], 0, s[78:79]
	s_addk_i32 s13, 0x400
	s_mov_b32 m0, s13
	s_nop 0
	global_load_lds_dwordx4 v[54:55], off
	v_lshl_add_u64 v[50:51], v[32:33], 0, s[42:43]
	v_lshl_add_u64 v[58:59], v[52:53], 0, s[16:17]
	s_add_i32 s12, s12, s9
	s_mov_b32 m0, s12
	s_nop 0
	global_load_lds_dwordx4 v[58:59], off
	v_lshl_add_u64 v[54:55], v[50:51], 0, s[78:79]
	s_add_i32 s13, s12, 0x400
	s_mov_b32 m0, s13
	s_nop 0
	global_load_lds_dwordx4 v[54:55], off
	v_lshl_add_u64 v[52:53], v[52:53], 0, s[82:83]
	s_add_i32 s13, s12, 0x800
	s_mov_b32 m0, s13
	s_nop 0
	global_load_lds_dwordx4 v[52:53], off
	v_lshl_add_u64 v[50:51], v[50:51], 0, s[18:19]
	s_addk_i32 s12, 0xc00
	s_mov_b32 m0, s12
	s_nop 0
	global_load_lds_dwordx4 v[50:51], off
	s_add_u32 s42, s42, 0x80
	s_addc_u32 s43, s43, 0
; DI void st_bf4(u16* p, float a, float b, float c, float d) { *(uint2*)p = make_uint2(pk2(a, b), pk2(c, d)); }
; template <int MT, class Epi>
; DI void gemm_tile(const u16* __restrict__ X, long ldx, const u16* __restrict__ W, long ldw, int K, char* smem,
;                   int m0, int n0, const Epi& epi, bool pre = false, const u16* Xn = nullptr, const u16* Wn = nullptr) {
;     ...
;   do {
;     asm volatile("s_waitcnt vmcnt(0)" ::: "memory");
;     __syncthreads();
;     if (kt + 1 < nk) GT_DMA((unsigned)((kt + 1) & 1) * 32768u)
;     else if (Xn != nullptr) { xe = Xn + oxe; xo = Xn + oxo; we = Wn + owe; wo = Wn + owo; GT_DMA(0u) }
;     const char* cur = smem + (kt & 1) * 32768;
; #pragma unroll
;     for (int ks = 0; ks < 2; ++ks) {
;       bf16x8 xf[MT], wf[4];
;       const int ch = ((ks * 4 + g) ^ rsw) << 4;
; #pragma unroll
;       for (int i = 0; i < MT; ++i) xf[i] = *(const bf16x8*)(cur + (wm * 16 * MT + i * 16 + lr) * 128 + ch);
; #pragma unroll
;       for (int i = 0; i < 4; ++i) wf[i] = *(const bf16x8*)(cur + 16384 + (wn * 64 + i * 16 + lr) * 128 + ch);
; #pragma unroll
;       for (int nt = 0; nt < 4; ++nt)
; #pragma unroll
;         for (int mt = 0; mt < MT; ++mt)
;           acc[nt][mt] = __builtin_amdgcn_mfma_f32_16x16x32_bf16(wf[nt], xf[mt], acc[nt][mt], 0, 0, 0);
;     }
;   } while (++kt < nk);
;     ...
;   epi.run(acc, m0 + wm * 16 * MT + lr, n0 + wn * 64 + 4 * g);
;   template <int NT, int MT> DI void run(f32x4 (&acc)[NT][MT], int mb, int nb) const {
; #pragma unroll
;     for (int nt = 0; nt < NT; ++nt)
; #pragma unroll
;       for (int mt = 0; mt < MT; ++mt) {
;         f32x4 v = acc[nt][mt];
;         st_bf4(C + (size_t)(mb + mt * 16) * ldc + nb + nt * 16, v[0], v[1], v[2], v[3]);
;       }
.LBB0_1135:
	s_add_i32 s12, s10, 0xc000
	s_add_i32 s11, s12, 0xfffee000
	s_cmp_lt_u32 s12, 0x12000
	s_cselect_b32 s12, s12, s11
	s_add_i32 s11, s10, 0x6000
	s_cmp_eq_u32 s11, 0x12000
	s_cselect_b32 s11, 0, s11
	v_lshl_add_u64 v[54:55], v[36:37], 0, s[42:43]
	v_lshl_add_u64 v[56:57], v[38:39], 0, s[42:43]
	s_waitcnt vmcnt(6)
	s_barrier
	s_cmp_eq_u32 s42, 0xf80
	s_cbranch_scc1 .Lst3_skip_3
	s_add_i32 s13, s12, s8
	s_mov_b32 m0, s13
	s_nop 0
	global_load_lds_dwordx4 v[56:57], off
	v_lshl_add_u64 v[52:53], v[34:35], 0, s[42:43]
	v_lshl_add_u64 v[54:55], v[54:55], 0, s[78:79]
	s_addk_i32 s13, 0x400
	s_mov_b32 m0, s13
	s_nop 0
	global_load_lds_dwordx4 v[54:55], off
	v_lshl_add_u64 v[50:51], v[32:33], 0, s[42:43]
	v_lshl_add_u64 v[58:59], v[52:53], 0, s[16:17]
	s_add_i32 s12, s12, s9
	s_mov_b32 m0, s12
	s_nop 0
	global_load_lds_dwordx4 v[58:59], off
	v_lshl_add_u64 v[54:55], v[50:51], 0, s[78:79]
	s_add_i32 s13, s12, 0x400
	s_mov_b32 m0, s13
	s_nop 0
	global_load_lds_dwordx4 v[54:55], off
	v_lshl_add_u64 v[52:53], v[52:53], 0, s[82:83]
	s_add_i32 s13, s12, 0x800
	s_mov_b32 m0, s13
	s_nop 0
	global_load_lds_dwordx4 v[52:53], off
	v_lshl_add_u64 v[50:51], v[50:51], 0, s[18:19]
	s_addk_i32 s12, 0xc00
	s_mov_b32 m0, s12
	s_nop 0
	global_load_lds_dwordx4 v[50:51], off
.Lst3_skip_3:
	v_or_b32_e32 v49, s10, v48
	v_add3_u32 v54, v49, v47, v44
	v_add3_u32 v49, v49, v45, v44
	ds_read_b128 v[50:53], v54
	ds_read_b128 v[54:57], v54 offset:2048
	ds_read_b128 v[58:61], v49 offset:8192
	ds_read_b128 v[62:65], v49 offset:10240
	ds_read_b128 v[66:69], v49 offset:12288
	ds_read_b128 v[70:73], v49 offset:14336
	v_or_b32_e32 v49, s10, v46
	s_waitcnt lgkmcnt(3)
	v_mfma_f32_16x16x32_bf16 v[24:27], v[58:61], v[54:57], v[24:27]
	s_add_u32 s42, s42, 0x80
	s_addc_u32 s43, s43, 0
	s_cmpk_lg_i32 s42, 0x1000
	s_waitcnt lgkmcnt(2)
	v_mfma_f32_16x16x32_bf16 v[16:19], v[62:65], v[54:57], v[16:19]
	s_mov_b32 s10, s11
	s_waitcnt lgkmcnt(1)
	v_mfma_f32_16x16x32_bf16 v[8:11], v[66:69], v[54:57], v[8:11]
	s_waitcnt lgkmcnt(0)
	v_mfma_f32_16x16x32_bf16 v[0:3], v[70:73], v[54:57], v[0:3]
	v_add3_u32 v54, v49, v47, v44
	v_add3_u32 v49, v49, v45, v44
	v_mfma_f32_16x16x32_bf16 v[28:31], v[58:61], v[50:53], v[28:31]
	v_mfma_f32_16x16x32_bf16 v[20:23], v[62:65], v[50:53], v[20:23]
	v_mfma_f32_16x16x32_bf16 v[12:15], v[66:69], v[50:53], v[12:15]
	v_mfma_f32_16x16x32_bf16 v[4:7], v[70:73], v[50:53], v[4:7]
	ds_read_b128 v[50:53], v54
	ds_read_b128 v[54:57], v54 offset:2048
	ds_read_b128 v[58:61], v49 offset:8192
	ds_read_b128 v[62:65], v49 offset:10240
	ds_read_b128 v[66:69], v49 offset:12288
	ds_read_b128 v[70:73], v49 offset:14336
	s_waitcnt lgkmcnt(3)
	v_mfma_f32_16x16x32_bf16 v[28:31], v[58:61], v[50:53], v[28:31]
	v_mfma_f32_16x16x32_bf16 v[24:27], v[58:61], v[54:57], v[24:27]
	s_waitcnt lgkmcnt(2)
	v_mfma_f32_16x16x32_bf16 v[20:23], v[62:65], v[50:53], v[20:23]
	v_mfma_f32_16x16x32_bf16 v[16:19], v[62:65], v[54:57], v[16:19]
	s_waitcnt lgkmcnt(1)
	v_mfma_f32_16x16x32_bf16 v[12:15], v[66:69], v[50:53], v[12:15]
	v_mfma_f32_16x16x32_bf16 v[8:11], v[66:69], v[54:57], v[8:11]
	s_waitcnt lgkmcnt(0)
	v_mfma_f32_16x16x32_bf16 v[4:7], v[70:73], v[50:53], v[4:7]
	v_mfma_f32_16x16x32_bf16 v[0:3], v[70:73], v[54:57], v[0:3]
	s_cbranch_scc1 .LBB0_1135
	v_add3_u32 v36, v48, v47, v44
	v_add3_u32 v60, v48, v45, v44
	s_waitcnt vmcnt(0)
	s_barrier
	ds_read_b128 v[32:35], v36 offset:24576
	ds_read_b128 v[36:39], v36 offset:26624
	ds_read_b128 v[48:51], v60 offset:32768
	ds_read_b128 v[52:55], v60 offset:34816
	ds_read_b128 v[56:59], v60 offset:36864
	ds_read_b128 v[60:63], v60 offset:38912
	s_waitcnt lgkmcnt(3)
	v_mfma_f32_16x16x32_bf16 v[24:27], v[48:51], v[36:39], v[24:27]
	s_lshl_b32 s7, s7, 7
	v_readlane_b32 s8, v252, 33
	v_readlane_b32 s9, v252, 34
	s_waitcnt lgkmcnt(2)
	v_mfma_f32_16x16x32_bf16 v[16:19], v[52:55], v[36:39], v[16:19]
	s_waitcnt lgkmcnt(1)
	v_mfma_f32_16x16x32_bf16 v[12:15], v[56:59], v[32:35], v[12:15]
	v_mfma_f32_16x16x32_bf16 v[8:11], v[56:59], v[36:39], v[8:11]
	v_add3_u32 v56, v46, v45, v44
	s_waitcnt lgkmcnt(0)
	v_mfma_f32_16x16x32_bf16 v[0:3], v[60:63], v[36:39], v[0:3]
	v_add3_u32 v36, v46, v47, v44
	v_mfma_f32_16x16x32_bf16 v[28:31], v[48:51], v[32:35], v[28:31]
	v_mfma_f32_16x16x32_bf16 v[20:23], v[52:55], v[32:35], v[20:23]
	v_mfma_f32_16x16x32_bf16 v[4:7], v[60:63], v[32:35], v[4:7]
	ds_read_b128 v[32:35], v36 offset:24576
	ds_read_b128 v[36:39], v36 offset:26624
	ds_read_b128 v[44:47], v56 offset:32768
	ds_read_b128 v[48:51], v56 offset:34816
	ds_read_b128 v[52:55], v56 offset:36864
	ds_read_b128 v[56:59], v56 offset:38912
	s_waitcnt lgkmcnt(3)
	v_mfma_f32_16x16x32_bf16 v[28:31], v[44:47], v[32:35], v[28:31]
	s_waitcnt lgkmcnt(2)
	v_mfma_f32_16x16x32_bf16 v[20:23], v[48:51], v[32:35], v[20:23]
	s_nop 5
	v_cvt_pk_bf16_f32 v28, v28, v29
	v_cvt_pk_bf16_f32 v29, v30, v31
	s_waitcnt lgkmcnt(1)
	v_mfma_f32_16x16x32_bf16 v[12:15], v[52:55], v[32:35], v[12:15]
	s_waitcnt lgkmcnt(0)
	v_mfma_f32_16x16x32_bf16 v[4:7], v[56:59], v[32:35], v[4:7]
	v_lshlrev_b32_e32 v32, 5, v40
	v_or3_b32 v182, v32, s40, v41
	v_lshl_add_u32 v32, v43, 6, s7
	v_lshl_or_b32 v32, v42, 2, v32
	v_ashrrev_i32_e32 v33, 31, v32
	v_lshlrev_b64 v[34:35], 11, v[182:183]
	v_mfma_f32_16x16x32_bf16 v[24:27], v[44:47], v[36:39], v[24:27]
	v_lshl_add_u64 v[34:35], s[8:9], 0, v[34:35]
	v_lshlrev_b64 v[32:33], 1, v[32:33]
	v_lshl_add_u64 v[34:35], v[34:35], 0, v[32:33]
	v_mfma_f32_16x16x32_bf16 v[16:19], v[48:51], v[36:39], v[16:19]
	v_or_b32_e32 v182, 16, v182
	global_store_dwordx2 v[34:35], v[28:29], off
	v_lshlrev_b64 v[28:29], 11, v[182:183]
	v_mfma_f32_16x16x32_bf16 v[8:11], v[52:55], v[36:39], v[8:11]
	v_lshl_add_u64 v[28:29], s[8:9], 0, v[28:29]
	v_lshl_add_u64 v[28:29], v[28:29], 0, v[32:33]
	v_cvt_pk_bf16_f32 v24, v24, v25
	v_mfma_f32_16x16x32_bf16 v[0:3], v[56:59], v[36:39], v[0:3]
	v_cvt_pk_bf16_f32 v25, v26, v27
	v_cvt_pk_bf16_f32 v20, v20, v21
	v_cvt_pk_bf16_f32 v21, v22, v23
	v_cvt_pk_bf16_f32 v16, v16, v17
	v_cvt_pk_bf16_f32 v17, v18, v19
	v_cvt_pk_bf16_f32 v12, v12, v13
	v_cvt_pk_bf16_f32 v13, v14, v15
	v_cvt_pk_bf16_f32 v8, v8, v9
	v_cvt_pk_bf16_f32 v9, v10, v11
	v_cvt_pk_bf16_f32 v4, v4, v5
	v_cvt_pk_bf16_f32 v5, v6, v7
	v_cvt_pk_bf16_f32 v0, v0, v1
	v_cvt_pk_bf16_f32 v1, v2, v3
	s_mov_b64 s[40:41], 0
	global_store_dwordx2 v[28:29], v[24:25], off
	global_store_dwordx2 v[34:35], v[20:21], off offset:32
	global_store_dwordx2 v[28:29], v[16:17], off offset:32
	global_store_dwordx2 v[34:35], v[12:13], off offset:64
	global_store_dwordx2 v[28:29], v[8:9], off offset:64
	global_store_dwordx2 v[34:35], v[4:5], off offset:96
	global_store_dwordx2 v[28:29], v[0:1], off offset:96
